# per-XCD start offset widened (s_sleep 127 per XCD index)
# speedup vs baseline: 1.0018x; 1.0018x over previous
; __device__ __forceinline__ const float* inp(const Args& a, int i) { asm volatile("" : "+s"(i)); return a.in[i]; }
; __device__ __forceinline__ unsigned char* wsp(const Args& a, size_t off) { asm volatile("" : "+s"(off)); return a.ws + off; }
; __global__ void __launch_bounds__(512, 2) fwd_megakernel(Args a) {
;     ...
;     for (int s = a.lo; s < a.hi; ++s) {
;         int tid = threadIdx.x; asm volatile("" : "+v"(tid));
;         const int lane = tid & 63, wave = __builtin_amdgcn_readfirstlane(tid >> 6), gw = bid * 8 + wave;
;         if (s == 0) {
;             prep_weights(a, lds, gw, ngw, wave, lane);
;             x_rows_prep(inp(a, I_X), (bf16_t*)wsp(a, WS_XN), (float*)wsp(a, WS_SSP_MIX), gw, ngw, lane);
.Lstag_loop:
	s_sleep 127
	s_sub_u32 s2, s2, 1
	s_cmp_lg_u32 s2, 0
	s_cbranch_scc1 .Lstag_loop
